# mLSTM gate scans on wave 0 use row-masked DPP adds and maxes (no select per step); duplicate KWT tile reads removed in the GLA state update
# baseline (speedup 1.0000x reference)
.LBB0_411:
	s_or_b64 exec, exec, s[78:79]
	s_mul_i32 s38, s36, 0x2d00
	s_add_i32 s37, s37, s38
	v_add3_u32 v42, s37, v77, v76
	s_waitcnt vmcnt(2)
	ds_write_b16 v42, v12 offset:36864
	ds_write_b16_d16_hi v42, v12 offset:37008
	ds_write_b16 v42, v13 offset:37152
	ds_write_b16_d16_hi v42, v13 offset:37296
	ds_write_b16 v42, v14 offset:37440
	ds_write_b16_d16_hi v42, v14 offset:37584
	ds_write_b16 v42, v15 offset:37728
	ds_write_b16_d16_hi v42, v15 offset:37872
	s_and_saveexec_b64 s[76:77], s[46:47]
	s_cbranch_execz .LBB0_413
	s_waitcnt vmcnt(0)
	v_add_f32_e32 v42, v68, v83
	v_min_f32_e32 v43, 0, v42
	v_mul_f32_e64 v42, |v42|, s19
	v_exp_f32_e32 v42, v42
	s_waitcnt lgkmcnt(10)
	v_add_f32_e32 v40, v40, v41
	v_add_f32_e32 v41, v67, v82
	v_add_f32_e32 v42, 1.0, v42
	v_log_f32_e32 v42, v42
	s_mulk_i32 s36, 0x7c00
	s_nop 0
	v_fmac_f32_e32 v43, 0xbf317218, v42
	s_nop 1
	v_add_f32_dpp v43, v43, v43 row_shr:1 row_mask:0xf bank_mask:0xf
	s_nop 1
	v_add_f32_dpp v43, v43, v43 row_shr:2 row_mask:0xf bank_mask:0xf
	s_nop 1
	v_add_f32_dpp v43, v43, v43 row_shr:4 row_mask:0xf bank_mask:0xf
	s_nop 1
	v_add_f32_dpp v43, v43, v43 row_shr:8 row_mask:0xf bank_mask:0xf
	s_nop 1
	v_add_f32_dpp v43, v43, v43 row_bcast:15 row_mask:0xa bank_mask:0xf
	s_nop 1
	v_add_f32_dpp v43, v43, v43 row_bcast:31 row_mask:0xc bank_mask:0xf
	s_nop 0
	v_sub_f32_e32 v41, v41, v43
	v_mov_b32_e32 v42, v41
	s_nop 1
	v_max_f32_dpp v42, v42, v42 row_shr:1 row_mask:0xf bank_mask:0xf
	s_nop 1
	v_max_f32_dpp v42, v42, v42 row_shr:2 row_mask:0xf bank_mask:0xf
	s_nop 1
	v_max_f32_dpp v42, v42, v42 row_shr:4 row_mask:0xf bank_mask:0xf
	s_nop 1
	v_max_f32_dpp v42, v42, v42 row_shr:8 row_mask:0xf bank_mask:0xf
	s_nop 1
	v_max_f32_dpp v42, v42, v42 row_bcast:15 row_mask:0xa bank_mask:0xf
	s_nop 1
	v_max_f32_dpp v42, v42, v42 row_bcast:31 row_mask:0xc bank_mask:0xf
	s_nop 0
	v_max_f32_e32 v40, v42, v40
	v_add_u32_e32 v44, s36, v98
	ds_write_b32 v44, v43
	v_add_u32_e32 v44, s36, v99
	ds_write_b32 v44, v41
	v_add_u32_e32 v44, s36, v100
	v_readlane_b32 s37, v40, 63
	ds_write_b32 v44, v40
	s_nop 0
	v_subrev_f32_e32 v40, s37, v41
	v_mul_f32_e32 v40, 0x3fb8aa3b, v40
	v_exp_f32_e32 v40, v40
	v_add_u32_e32 v41, s36, v101
	ds_write_b32 v41, v40

.LBB0_494:
	s_add_i32 s37, s16, 0xffffff00
	s_cmp_lt_u32 s29, 4
	s_mul_i32 s36, s35, 0x13a00
	s_mul_i32 s8, s35, 0x10200
	s_mul_i32 s9, s35, 0xa200
	s_cselect_b32 s35, s16, s37
	v_add_u32_e32 v75, s35, v64
	s_cselect_b32 s35, 0xff, s22
	v_sub_u32_e32 v76, s35, v75
	v_cndmask_b32_e32 v75, v76, v75, vcc
	s_cselect_b32 s35, s28, s17
	v_add_u32_e32 v76, s35, v75
	v_add_u32_e32 v90, s36, v66
	v_ashrrev_i32_e32 v77, 31, v76
	v_add_u32_e32 v75, v90, v71
	s_waitcnt lgkmcnt(0)
	s_barrier
	ds_read_b128 v[132:135], v65 offset:55296
	ds_read_b128 v[136:139], v65 offset:55360
	ds_read_b128 v[140:143], v75 offset:18432
	ds_read_b128 v[144:147], v75 offset:18496
	v_add_u32_e32 v129, v90, v72
	ds_read_b128 v[148:151], v129 offset:18432
	ds_read_b128 v[152:155], v129 offset:18496
	v_add_u32_e32 v131, s34, v59
	ds_read_b128 v[172:175], v131 offset:0
	ds_read_b128 v[176:179], v131 offset:16
	ds_read_b128 v[180:183], v131 offset:32
	ds_read_b128 v[184:187], v131 offset:48
	ds_read_b128 v[188:191], v131 offset:64
	ds_read_b128 v[192:195], v131 offset:80
	ds_read_b128 v[196:199], v131 offset:96
	ds_read_b128 v[200:203], v131 offset:112
	v_lshlrev_b64 v[88:89], 11, v[76:77]
	s_waitcnt lgkmcnt(10)
	v_mfma_f32_16x16x32_bf16 v[28:31], v[140:143], v[132:135], v[28:31]
	v_mfma_f32_16x16x32_bf16 v[28:31], v[144:147], v[136:139], v[28:31]
	s_nop 7
	v_cvt_pk_bf16_f32 v28, v28, v29
	v_cvt_pk_bf16_f32 v29, v30, v31
	v_lshl_add_u64 v[30:31], v[52:53], 0, v[88:89]
	global_store_dwordx2 v[30:31], v[28:29], off
	v_add_u32_e32 v28, v90, v72
	s_waitcnt lgkmcnt(8)
	v_mfma_f32_16x16x32_bf16 v[24:27], v[148:151], v[132:135], v[24:27]
	v_mfma_f32_16x16x32_bf16 v[24:27], v[152:155], v[136:139], v[24:27]
	s_nop 7
	v_cvt_pk_bf16_f32 v24, v24, v25
	v_cvt_pk_bf16_f32 v25, v26, v27
	global_store_dwordx2 v[30:31], v[24:25], off offset:32
	s_waitcnt lgkmcnt(5)
	v_pk_mul_f32 v[156:157], v[172:173], v[204:205]
	v_pk_mul_f32 v[158:159], v[174:175], v[206:207]
	v_pk_fma_f32 v[156:157], v[176:177], v[208:209], v[156:157]
	v_pk_fma_f32 v[158:159], v[178:179], v[210:211], v[158:159]
	v_pk_fma_f32 v[156:157], v[180:181], v[212:213], v[156:157]
	v_pk_fma_f32 v[158:159], v[182:183], v[214:215], v[158:159]
	s_waitcnt lgkmcnt(4)
	v_pk_fma_f32 v[156:157], v[184:185], v[216:217], v[156:157]
	v_pk_fma_f32 v[158:159], v[186:187], v[218:219], v[158:159]
	ds_read_b128 v[172:175], v131 offset:128
	ds_read_b128 v[176:179], v131 offset:144
	ds_read_b128 v[180:183], v131 offset:160
	ds_read_b128 v[184:187], v131 offset:176
	v_pk_add_f32 v[156:157], v[156:157], v[158:159]
	s_waitcnt lgkmcnt(6)
	v_pk_mul_f32 v[160:161], v[188:189], v[204:205]
	v_add_f32_e32 v164, v156, v157
	v_pk_mul_f32 v[162:163], v[190:191], v[206:207]
	v_add_f32_e32 v164, v54, v164
	v_pk_fma_f32 v[160:161], v[192:193], v[208:209], v[160:161]
	v_min_f32_e32 v166, 0, v164
	v_pk_fma_f32 v[162:163], v[194:195], v[210:211], v[162:163]
	v_mul_f32_e64 v164, |v164|, s19
	s_waitcnt lgkmcnt(4)
	v_pk_fma_f32 v[160:161], v[196:197], v[212:213], v[160:161]
	v_exp_f32_e32 v164, v164
	v_pk_fma_f32 v[162:163], v[198:199], v[214:215], v[162:163]
	v_pk_fma_f32 v[160:161], v[200:201], v[216:217], v[160:161]
	v_add_f32_e32 v164, 1.0, v164
	v_pk_fma_f32 v[162:163], v[202:203], v[218:219], v[162:163]
	v_log_f32_e32 v164, v164
	ds_read_b128 v[188:191], v131 offset:192
	ds_read_b128 v[192:195], v131 offset:208
	v_fmac_f32_e32 v166, 0xbf317218, v164
	ds_read_b128 v[196:199], v131 offset:224
	v_fma_f32 v25, v166, s26, 0
	ds_read_b128 v[200:203], v131 offset:240
	v_pk_add_f32 v[160:161], v[160:161], v[162:163]
	s_waitcnt lgkmcnt(6)
	v_pk_mul_f32 v[156:157], v[172:173], v[204:205]
	v_add_f32_e32 v165, v160, v161
	v_pk_mul_f32 v[158:159], v[174:175], v[206:207]
	v_add_f32_e32 v165, v54, v165
	v_pk_fma_f32 v[156:157], v[176:177], v[208:209], v[156:157]
	v_min_f32_e32 v167, 0, v165
	v_pk_fma_f32 v[158:159], v[178:179], v[210:211], v[158:159]
	v_mul_f32_e64 v165, |v165|, s19
	s_waitcnt lgkmcnt(4)
	v_pk_fma_f32 v[156:157], v[180:181], v[212:213], v[156:157]
	v_exp_f32_e32 v165, v165
	v_pk_fma_f32 v[158:159], v[182:183], v[214:215], v[158:159]
	v_pk_fma_f32 v[156:157], v[184:185], v[216:217], v[156:157]
	v_add_f32_e32 v165, 1.0, v165
	v_pk_fma_f32 v[158:159], v[186:187], v[218:219], v[158:159]
	v_log_f32_e32 v165, v165
	ds_read_b128 v[172:175], v131 offset:256
	ds_read_b128 v[176:179], v131 offset:272
	v_fmac_f32_e32 v167, 0xbf317218, v165
	ds_read_b128 v[180:183], v131 offset:288
	v_fmamk_f32 v26, v167, 0x3d800000, v25
	ds_read_b128 v[184:187], v131 offset:304
	v_pk_add_f32 v[156:157], v[156:157], v[158:159]
	s_waitcnt lgkmcnt(6)
	v_pk_mul_f32 v[160:161], v[188:189], v[204:205]
	v_add_f32_e32 v164, v156, v157
	v_pk_mul_f32 v[162:163], v[190:191], v[206:207]
	v_add_f32_e32 v164, v54, v164
	v_pk_fma_f32 v[160:161], v[192:193], v[208:209], v[160:161]
	v_min_f32_e32 v166, 0, v164
	v_pk_fma_f32 v[162:163], v[194:195], v[210:211], v[162:163]
	v_mul_f32_e64 v164, |v164|, s19
	s_waitcnt lgkmcnt(4)
	v_pk_fma_f32 v[160:161], v[196:197], v[212:213], v[160:161]
	v_exp_f32_e32 v164, v164
	v_pk_fma_f32 v[162:163], v[198:199], v[214:215], v[162:163]
	v_pk_fma_f32 v[160:161], v[200:201], v[216:217], v[160:161]
	v_add_f32_e32 v164, 1.0, v164
	v_pk_fma_f32 v[162:163], v[202:203], v[218:219], v[162:163]
	v_log_f32_e32 v164, v164
	ds_read_b128 v[188:191], v131 offset:320
	ds_read_b128 v[192:195], v131 offset:336
	v_fmac_f32_e32 v166, 0xbf317218, v164
	ds_read_b128 v[196:199], v131 offset:352
	v_fmamk_f32 v29, v166, 0x3d800000, v26
	ds_read_b128 v[200:203], v131 offset:368
	v_pk_add_f32 v[160:161], v[160:161], v[162:163]
	s_waitcnt lgkmcnt(6)
	v_pk_mul_f32 v[156:157], v[172:173], v[204:205]
	v_add_f32_e32 v165, v160, v161
	v_pk_mul_f32 v[158:159], v[174:175], v[206:207]
	v_add_f32_e32 v165, v54, v165
	v_pk_fma_f32 v[156:157], v[176:177], v[208:209], v[156:157]
	v_min_f32_e32 v167, 0, v165
	v_pk_fma_f32 v[158:159], v[178:179], v[210:211], v[158:159]
	v_mul_f32_e64 v165, |v165|, s19
	s_waitcnt lgkmcnt(4)
	v_pk_fma_f32 v[156:157], v[180:181], v[212:213], v[156:157]
	v_exp_f32_e32 v165, v165
	v_pk_fma_f32 v[158:159], v[182:183], v[214:215], v[158:159]
	v_pk_fma_f32 v[156:157], v[184:185], v[216:217], v[156:157]
	v_add_f32_e32 v165, 1.0, v165
	v_pk_fma_f32 v[158:159], v[186:187], v[218:219], v[158:159]
	v_log_f32_e32 v165, v165
	ds_read_b128 v[172:175], v131 offset:384
	ds_read_b128 v[176:179], v131 offset:400
	v_fmac_f32_e32 v167, 0xbf317218, v165
	ds_read_b128 v[180:183], v131 offset:416
	v_fmamk_f32 v30, v167, 0x3d800000, v29
	ds_read_b128 v[184:187], v131 offset:432
	v_pk_add_f32 v[156:157], v[156:157], v[158:159]
	s_waitcnt lgkmcnt(6)
	v_pk_mul_f32 v[160:161], v[188:189], v[204:205]
	v_add_f32_e32 v164, v156, v157
	v_pk_mul_f32 v[162:163], v[190:191], v[206:207]
	v_add_f32_e32 v164, v54, v164
	v_pk_fma_f32 v[160:161], v[192:193], v[208:209], v[160:161]
	v_min_f32_e32 v166, 0, v164
	v_pk_fma_f32 v[162:163], v[194:195], v[210:211], v[162:163]
	v_mul_f32_e64 v164, |v164|, s19
	s_waitcnt lgkmcnt(4)
	v_pk_fma_f32 v[160:161], v[196:197], v[212:213], v[160:161]
	v_exp_f32_e32 v164, v164
	v_pk_fma_f32 v[162:163], v[198:199], v[214:215], v[162:163]
	v_pk_fma_f32 v[160:161], v[200:201], v[216:217], v[160:161]
	v_add_f32_e32 v164, 1.0, v164
	v_pk_fma_f32 v[162:163], v[202:203], v[218:219], v[162:163]
	v_log_f32_e32 v164, v164
	ds_read_b128 v[188:191], v131 offset:448
	ds_read_b128 v[192:195], v131 offset:464
	v_fmac_f32_e32 v166, 0xbf317218, v164
	ds_read_b128 v[196:199], v131 offset:480
	v_fmamk_f32 v31, v166, 0x3d800000, v30
	ds_read_b128 v[200:203], v131 offset:496
	v_pk_add_f32 v[160:161], v[160:161], v[162:163]
	s_waitcnt lgkmcnt(6)
	v_pk_mul_f32 v[156:157], v[172:173], v[204:205]
	v_add_f32_e32 v165, v160, v161
	v_pk_mul_f32 v[158:159], v[174:175], v[206:207]
	v_add_f32_e32 v165, v54, v165
	v_pk_fma_f32 v[156:157], v[176:177], v[208:209], v[156:157]
	v_min_f32_e32 v167, 0, v165
	v_pk_fma_f32 v[158:159], v[178:179], v[210:211], v[158:159]
	v_mul_f32_e64 v165, |v165|, s19
	s_waitcnt lgkmcnt(4)
	v_pk_fma_f32 v[156:157], v[180:181], v[212:213], v[156:157]
	v_exp_f32_e32 v165, v165
	v_pk_fma_f32 v[158:159], v[182:183], v[214:215], v[158:159]
	v_pk_fma_f32 v[156:157], v[184:185], v[216:217], v[156:157]
	v_add_f32_e32 v165, 1.0, v165
	v_pk_fma_f32 v[158:159], v[186:187], v[218:219], v[158:159]
	v_log_f32_e32 v165, v165
	s_nop 0
	v_fmac_f32_e32 v167, 0xbf317218, v165
	v_fmamk_f32 v76, v167, 0x3d800000, v31
	v_pk_add_f32 v[156:157], v[156:157], v[158:159]
	s_waitcnt lgkmcnt(2)
	v_pk_mul_f32 v[160:161], v[188:189], v[204:205]
	v_add_f32_e32 v164, v156, v157
	v_pk_mul_f32 v[162:163], v[190:191], v[206:207]
	v_add_f32_e32 v164, v54, v164
	v_pk_fma_f32 v[160:161], v[192:193], v[208:209], v[160:161]
	v_min_f32_e32 v166, 0, v164
	v_pk_fma_f32 v[162:163], v[194:195], v[210:211], v[162:163]
	v_mul_f32_e64 v164, |v164|, s19
	s_waitcnt lgkmcnt(0)
	v_pk_fma_f32 v[160:161], v[196:197], v[212:213], v[160:161]
	v_exp_f32_e32 v164, v164
	v_pk_fma_f32 v[162:163], v[198:199], v[214:215], v[162:163]
	v_pk_fma_f32 v[160:161], v[200:201], v[216:217], v[160:161]
	v_add_f32_e32 v164, 1.0, v164
	v_pk_fma_f32 v[162:163], v[202:203], v[218:219], v[162:163]
	v_log_f32_e32 v164, v164
	s_nop 0
	v_fmac_f32_e32 v166, 0xbf317218, v164
	v_fmamk_f32 v77, v166, 0x3d800000, v76
	v_pk_add_f32 v[160:161], v[160:161], v[162:163]
	s_nop 0
	v_add_f32_e32 v165, v160, v161
	v_add_f32_e32 v165, v54, v165
	v_min_f32_e32 v167, 0, v165
	v_mul_f32_e64 v165, |v165|, s19
	v_exp_f32_e32 v165, v165
	s_nop 0
	v_add_f32_e32 v165, 1.0, v165
	v_log_f32_e32 v165, v165
	s_nop 0
	v_fmac_f32_e32 v167, 0xbf317218, v165
	v_fmamk_f32 v78, v167, 0x3d800000, v77
	v_add_u32_e32 v79, s31, v62
	v_add_u32_e32 v24, s9, v69
	ds_write_b32 v60, v78
	s_waitcnt lgkmcnt(0)
	s_barrier
	ds_read_b128 v[132:135], v24
	v_add_u32_e32 v129, s8, v65
	ds_read_b128 v[136:139], v129 offset:46080
	ds_read_b128 v[140:143], v75 offset:18432
	ds_read_b128 v[144:147], v129 offset:46144
	ds_read_b128 v[148:151], v75 offset:18496
	ds_read_b128 v[152:155], v28 offset:18432
	ds_read_b128 v[156:159], v28 offset:18496
	v_add_u32_e32 v27, v70, v71
	s_mul_i32 s8, s30, 0x10200
	s_waitcnt lgkmcnt(4)
	v_pk_mul_f32 v[16:17], v[16:17], v[132:133]
	v_pk_mul_f32 v[18:19], v[18:19], v[134:135]
	v_pk_mul_f32 v[20:21], v[20:21], v[132:133]
	v_pk_mul_f32 v[22:23], v[22:23], v[134:135]
	v_mfma_f32_16x16x32_bf16 v[16:19], v[136:139], v[140:143], v[16:19]
	s_waitcnt lgkmcnt(2)
	v_mfma_f32_16x16x32_bf16 v[16:19], v[144:147], v[148:151], v[16:19]
	s_nop 7
	v_cvt_pk_bf16_f32 v84, v16, v17
	v_cvt_pk_bf16_f32 v85, v18, v19
	ds_write_b64 v27, v[84:85] offset:64512
	s_waitcnt lgkmcnt(1)
	v_mfma_f32_16x16x32_bf16 v[20:23], v[136:139], v[152:155], v[20:23]
	v_add_u32_e32 v24, v70, v72
	v_mfma_f32_16x16x32_bf16 v[20:23], v[144:147], v[156:159], v[20:23]
	ds_read2st64_b32 v[130:131], v61 offset1:1
	ds_read2st64_b32 v[160:161], v61 offset0:2 offset1:3
	ds_read2st64_b32 v[162:163], v61 offset0:4 offset1:5
	ds_read2st64_b32 v[164:165], v61 offset0:6 offset1:7
	ds_read_u16 v166, v79
	ds_read_u16 v167, v79 offset:9216
	ds_read_u16 v172, v79 offset:144
	ds_read_u16 v173, v79 offset:9360
	ds_read_u16 v174, v79 offset:288
	ds_read_u16 v175, v79 offset:9504
	ds_read_u16 v176, v79 offset:432
	ds_read_u16 v177, v79 offset:9648
	ds_read_u16 v178, v79 offset:576
	ds_read_u16 v179, v79 offset:9792
	ds_read_u16 v180, v79 offset:720
	ds_read_u16 v181, v79 offset:9936
	ds_read_u16 v182, v79 offset:864
	ds_read_u16 v183, v79 offset:10080
	ds_read_u16 v184, v79 offset:1008
	ds_read_u16 v185, v79 offset:10224
	s_nop 7
	v_cvt_pk_bf16_f32 v80, v20, v21
	v_cvt_pk_bf16_f32 v81, v22, v23
	ds_write_b64 v24, v[80:81] offset:64512
	s_waitcnt lgkmcnt(12)
	v_add_f32_e32 v24, 0, v130
	v_cndmask_b32_e64 v27, 0, v24, s[42:43]
	v_add_f32_e32 v28, v131, v27
	v_add_f32_e32 v24, v24, v131
	v_cndmask_b32_e64 v27, v27, v28, s[44:45]
	v_add_f32_e32 v28, v160, v27
	v_cndmask_b32_e64 v27, v27, v28, s[46:47]
	v_add_f32_e32 v24, v24, v160
	v_add_f32_e32 v28, v161, v27
	v_add_f32_e32 v24, v24, v161
	v_cndmask_b32_e64 v27, v27, v28, s[48:49]
	v_add_f32_e32 v28, v162, v27
	v_cndmask_b32_e64 v27, v27, v28, s[50:51]
	v_add_f32_e32 v24, v24, v162
	v_add_f32_e32 v28, v163, v27
	v_add_f32_e32 v24, v24, v163
	v_cndmask_b32_e64 v27, v27, v28, s[52:53]
	v_add_f32_e32 v28, v164, v27
	v_cndmask_b32_e64 v27, v27, v28, s[54:55]
	v_add_f32_e32 v28, v165, v27
	v_cndmask_b32_e64 v75, v27, v28, s[56:57]
	v_add_f32_e32 v25, v25, v75
	v_mul_f32_e32 v27, 0xbfb8aa3b, v25
	v_add_f32_e32 v24, v24, v164
	v_exp_f32_e32 v80, v27
	v_mul_f32_e32 v25, 0x3fb8aa3b, v25
	v_exp_f32_e32 v25, v25
	v_add_f32_e32 v24, v24, v165
	v_lshlrev_b32_e32 v27, 16, v166
	v_mul_f32_e32 v27, 0x3e000000, v27
	v_mul_f32_e32 v25, v27, v25
	v_cvt_pk_bf16_f32 v25, v25, s0
	ds_write_b16 v62, v25 offset:27648
	v_add_f32_e32 v25, v26, v75
	v_lshlrev_b32_e32 v82, 16, v167
	v_mul_f32_e32 v26, 0xbfb8aa3b, v25
	v_exp_f32_e32 v81, v26
	v_mul_f32_e32 v26, v80, v82
	v_cvt_pk_bf16_f32 v26, v26, s0
	ds_write_b16 v62, v26 offset:36864
	v_mul_f32_e32 v25, 0x3fb8aa3b, v25
	v_exp_f32_e32 v25, v25
	v_mul_f32_e32 v24, 0x3fb8aa3b, v24
	v_lshlrev_b32_e32 v26, 16, v172
	v_mul_f32_e32 v26, 0x3e000000, v26
	v_mul_f32_e32 v25, v26, v25
	v_exp_f32_e32 v24, v24
	v_lshlrev_b32_e32 v83, 16, v173
	v_cvt_pk_bf16_f32 v25, v25, s0
	ds_write_b16 v62, v25 offset:27792
	v_mul_f32_e32 v25, v81, v83
	v_cvt_pk_bf16_f32 v25, v25, s0
	ds_write_b16 v62, v25 offset:37008
	v_pk_mul_f32 v[26:27], v[24:25], v[80:81] op_sel_hi:[0,1]
	v_add_f32_e32 v25, v29, v75
	v_mul_f32_e32 v28, 0xbfb8aa3b, v25
	v_mul_f32_e32 v25, 0x3fb8aa3b, v25
	v_exp_f32_e32 v25, v25
	v_exp_f32_e32 v28, v28
	v_lshlrev_b32_e32 v29, 16, v174
	v_mul_f32_e32 v29, 0x3e000000, v29
	v_mul_f32_e32 v25, v25, v29
	s_waitcnt lgkmcnt(12)
	v_lshlrev_b32_e32 v80, 16, v175
	v_cvt_pk_bf16_f32 v25, v25, s0
	ds_write_b16 v62, v25 offset:27936
	v_add_f32_e32 v25, v30, v75
	v_mul_f32_e32 v30, v28, v80
	v_cvt_pk_bf16_f32 v30, v30, s0
	ds_write_b16 v62, v30 offset:37152
	v_mul_f32_e32 v29, 0xbfb8aa3b, v25
	v_mul_f32_e32 v25, 0x3fb8aa3b, v25
	v_exp_f32_e32 v25, v25
	v_exp_f32_e32 v29, v29
	v_lshlrev_b32_e32 v30, 16, v176
	v_mul_f32_e32 v30, 0x3e000000, v30
	v_mul_f32_e32 v25, v25, v30
	v_lshlrev_b32_e32 v81, 16, v177
	v_cvt_pk_bf16_f32 v25, v25, s0
	ds_write_b16 v62, v25 offset:28080
	v_mul_f32_e32 v25, v29, v81
	v_cvt_pk_bf16_f32 v25, v25, s0
	ds_write_b16 v62, v25 offset:37296
	v_pk_mul_f32 v[28:29], v[24:25], v[28:29] op_sel_hi:[0,1]
	v_add_f32_e32 v25, v31, v75
	v_mul_f32_e32 v30, 0xbfb8aa3b, v25
	v_mul_f32_e32 v25, 0x3fb8aa3b, v25
	v_pk_mul_f32 v[28:29], v[28:29], v[80:81]
	v_exp_f32_e32 v25, v25
	v_exp_f32_e32 v30, v30
	v_lshlrev_b32_e32 v31, 16, v178
	v_mul_f32_e32 v31, 0x3e000000, v31
	v_mul_f32_e32 v25, v25, v31
	s_waitcnt lgkmcnt(12)
	v_lshlrev_b32_e32 v80, 16, v179
	v_cvt_pk_bf16_f32 v25, v25, s0
	ds_write_b16 v62, v25 offset:28224
	v_add_f32_e32 v25, v76, v75
	v_mul_f32_e32 v76, v30, v80
	v_cvt_pk_bf16_f32 v76, v76, s0
	ds_write_b16 v62, v76 offset:37440
	v_mul_f32_e32 v31, 0xbfb8aa3b, v25
	v_mul_f32_e32 v25, 0x3fb8aa3b, v25
	v_exp_f32_e32 v25, v25
	v_exp_f32_e32 v31, v31
	v_lshlrev_b32_e32 v76, 16, v180
	v_mul_f32_e32 v76, 0x3e000000, v76
	v_mul_f32_e32 v25, v25, v76
	v_lshlrev_b32_e32 v81, 16, v181
	v_cvt_pk_bf16_f32 v25, v25, s0
	ds_write_b16 v62, v25 offset:28368
	v_mul_f32_e32 v25, v31, v81
	v_cvt_pk_bf16_f32 v25, v25, s0
	ds_write_b16 v62, v25 offset:37584
	v_pk_mul_f32 v[30:31], v[24:25], v[30:31] op_sel_hi:[0,1]
	v_add_f32_e32 v25, v77, v75
	v_mul_f32_e32 v76, 0xbfb8aa3b, v25
	v_mul_f32_e32 v25, 0x3fb8aa3b, v25
	v_exp_f32_e32 v25, v25
	v_pk_mul_f32 v[30:31], v[30:31], v[80:81]
	v_lshlrev_b32_e32 v77, 16, v182
	v_mul_f32_e32 v77, 0x3e000000, v77
	v_exp_f32_e32 v76, v76
	v_mul_f32_e32 v25, v25, v77
	v_cvt_pk_bf16_f32 v25, v25, s0
	ds_write_b16 v62, v25 offset:28512
	v_add_f32_e32 v25, v78, v75
	s_waitcnt lgkmcnt(12)
	v_lshlrev_b32_e32 v80, 16, v183
	v_mul_f32_e32 v75, 0xbfb8aa3b, v25
	v_exp_f32_e32 v77, v75
	v_mul_f32_e32 v75, v76, v80
	v_cvt_pk_bf16_f32 v75, v75, s0
	ds_write_b16 v62, v75 offset:37728
	v_mul_f32_e32 v25, 0x3fb8aa3b, v25
	v_exp_f32_e32 v25, v25
	v_pk_mul_f32 v[26:27], v[26:27], v[82:83]
	v_lshlrev_b32_e32 v75, 16, v184
	v_mul_f32_e32 v75, 0x3e000000, v75
	v_mul_f32_e32 v25, v25, v75
	v_lshlrev_b32_e32 v81, 16, v185
	v_cvt_pk_bf16_f32 v25, v25, s0
	ds_write_b16 v62, v25 offset:28656
	v_mul_f32_e32 v25, v77, v81
	v_cvt_pk_bf16_f32 v25, v25, s0
	v_pk_mul_f32 v[76:77], v[24:25], v[76:77] op_sel_hi:[0,1]
	v_pk_mul_f32 v[76:77], v[76:77], v[80:81]
	ds_write_b16 v62, v25 offset:37872
	v_cvt_pk_bf16_f32 v26, v26, v27
	v_cvt_pk_bf16_f32 v27, v28, v29
	v_cvt_pk_bf16_f32 v28, v30, v31
	v_cvt_pk_bf16_f32 v29, v76, v77
	v_add_u32_e32 v25, s8, v63
	ds_write_b128 v25, v[26:29] offset:46080
	s_and_saveexec_b64 s[8:9], s[58:59]
	s_cbranch_execz .LBB0_487
	s_mul_i32 s30, s30, 0xa200
	v_add_u32_e32 v25, s30, v67
	ds_write_b32 v25, v24
	s_branch .LBB0_487
